# speedup vs baseline: 1.0062x; 1.0062x over previous
; __device__ __forceinline__ void scan_phase(const ScanArgs& s, char* shm) {
;     ...
;       for (int c = 0; c < NCH + 2; ++c) {
;         if (c < NCH) {
;           float4* sr = (float4*)(shm + OFF_SRING + (c & 1) * (TC * 2048) + wid * 1024 + lane * 16);
;           const unsigned aj = lds0 + (unsigned)((c & 3) * VECBUF) + (unsigned)j * 16u, av = lds0 + (unsigned)((c & 3) * VECBUF) + 1024u + (unsigned)row * 8u;
;           f32x4 mkA, w4A, kaA, kmA, mkB, w4B, kaB, kmB, mkC, w4C, kaC, kmC; f32x2 vgA, vgB, vgC;
;     ...
;           SLOAD(A, 0); SLOAD(B, 1); SLOAD(C, 2);
;           SSTEP(A, 0); SSTEP(B, 1); SSTEP(C, 2); SSTEP(A, 3); SSTEP(B, 4); SSTEP(C, 5); SSTEP(A, 6); SSTEP(B, 7);
;           SSTEP(C, 8); SSTEP(A, 9); SSTEP(B, 10); SSTEP(C, 11); SSTEP(A, 12); SSTEP(B, 13); SSTEP(C, 14); SSTEP(A, 15);
.LBB0_172:
	s_cmpk_gt_u32 s56, 0x3ff
	s_cbranch_scc1 .LBB0_171
	s_and_b32 s57, s49, 0x8000
	v_add_u32_e32 v70, s57, v175
	s_and_b32 s57, s56, 3
	s_mulk_i32 s57, 0x4400
	v_or_b32_e32 v68, s57, v172
	v_add_u32_e32 v69, s57, v176
	ds_read_b128 v[12:15], v68 offset:0
	ds_read_b128 v[16:19], v68 offset:256
	ds_read_b128 v[20:23], v68 offset:512
	ds_read_b128 v[24:27], v68 offset:768
	ds_read_b64 v[60:61], v69 offset:0
	ds_read_b128 v[28:31], v68 offset:1088
	ds_read_b128 v[32:35], v68 offset:1344
	ds_read_b128 v[36:39], v68 offset:1600
	ds_read_b128 v[40:43], v68 offset:1856
	ds_read_b64 v[62:63], v69 offset:1088
	ds_read_b128 v[44:47], v68 offset:2176
	ds_read_b128 v[48:51], v68 offset:2432
	ds_read_b128 v[52:55], v68 offset:2688
	ds_read_b128 v[56:59], v68 offset:2944
	ds_read_b64 v[64:65], v69 offset:2176
	s_waitcnt lgkmcnt(10)
	v_add_f32_dpp v4, v7, v7 quad_perm:[1,0,3,2] row_mask:0xf bank_mask:0xf bound_ctrl:1
	v_pk_mul_f32 v[8:9], v[24:25], v[60:61] op_sel_hi:[1,0]
	v_pk_mul_f32 v[10:11], v[26:27], v[60:61] op_sel_hi:[1,0]
	v_add_f32_dpp v4, v4, v4 quad_perm:[2,3,0,1] row_mask:0xf bank_mask:0xf bound_ctrl:1
	v_pk_fma_f32 v[0:1], v[0:1], v[16:17], v[8:9]
	v_pk_fma_f32 v[2:3], v[2:3], v[18:19], v[10:11]
	v_add_f32_dpp v4, v4, v4 row_half_mirror row_mask:0xf bank_mask:0xf bound_ctrl:1
	v_pk_mul_f32 v[8:9], v[0:1], v[12:13]
	v_pk_fma_f32 v[8:9], v[2:3], v[14:15], v[8:9]
	v_add_f32_dpp v4, v4, v4 row_mirror row_mask:0xf bank_mask:0xf bound_ctrl:1
	v_add_f32_e32 v7, v8, v9
	v_fmac_f32_e32 v4, v6, v67
	v_pk_fma_f32 v[0:1], v[20:21], v[4:5], v[0:1] op_sel_hi:[1,0,1]
	v_pk_fma_f32 v[2:3], v[22:23], v[4:5], v[2:3] op_sel_hi:[1,0,1]
	ds_read_b128 v[12:15], v68 offset:3264
	ds_read_b128 v[16:19], v68 offset:3520
	ds_read_b128 v[20:23], v68 offset:3776
	ds_read_b128 v[24:27], v68 offset:4032
	ds_read_b64 v[66:67], v69 offset:3264
	ds_write_b128 v70, v[0:3] offset:0
	s_waitcnt lgkmcnt(11)
	v_add_f32_dpp v6, v7, v7 quad_perm:[1,0,3,2] row_mask:0xf bank_mask:0xf bound_ctrl:1
	v_pk_mul_f32 v[8:9], v[40:41], v[62:63] op_sel_hi:[1,0]
	v_pk_mul_f32 v[10:11], v[42:43], v[62:63] op_sel_hi:[1,0]
	v_add_f32_dpp v6, v6, v6 quad_perm:[2,3,0,1] row_mask:0xf bank_mask:0xf bound_ctrl:1
	v_pk_fma_f32 v[0:1], v[0:1], v[32:33], v[8:9]
	v_pk_fma_f32 v[2:3], v[2:3], v[34:35], v[10:11]
	v_add_f32_dpp v6, v6, v6 row_half_mirror row_mask:0xf bank_mask:0xf bound_ctrl:1
	v_pk_mul_f32 v[8:9], v[0:1], v[28:29]
	v_pk_fma_f32 v[8:9], v[2:3], v[30:31], v[8:9]
	v_add_f32_dpp v6, v6, v6 row_mirror row_mask:0xf bank_mask:0xf bound_ctrl:1
	v_add_f32_e32 v7, v8, v9
	v_fmac_f32_e32 v6, v4, v61
	v_pk_fma_f32 v[0:1], v[36:37], v[6:7], v[0:1] op_sel_hi:[1,0,1]
	v_pk_fma_f32 v[2:3], v[38:39], v[6:7], v[2:3] op_sel_hi:[1,0,1]
	ds_read_b128 v[28:31], v68 offset:4352
	ds_read_b128 v[32:35], v68 offset:4608
	ds_read_b128 v[36:39], v68 offset:4864
	ds_read_b128 v[40:43], v68 offset:5120
	ds_read_b64 v[60:61], v69 offset:4352
	ds_write_b128 v70, v[0:3] offset:2048
	s_waitcnt lgkmcnt(12)
	v_add_f32_dpp v4, v7, v7 quad_perm:[1,0,3,2] row_mask:0xf bank_mask:0xf bound_ctrl:1
	v_pk_mul_f32 v[8:9], v[56:57], v[64:65] op_sel_hi:[1,0]
	v_pk_mul_f32 v[10:11], v[58:59], v[64:65] op_sel_hi:[1,0]
	v_add_f32_dpp v4, v4, v4 quad_perm:[2,3,0,1] row_mask:0xf bank_mask:0xf bound_ctrl:1
	v_pk_fma_f32 v[0:1], v[0:1], v[48:49], v[8:9]
	v_pk_fma_f32 v[2:3], v[2:3], v[50:51], v[10:11]
	v_add_f32_dpp v4, v4, v4 row_half_mirror row_mask:0xf bank_mask:0xf bound_ctrl:1
	v_pk_mul_f32 v[8:9], v[0:1], v[44:45]
	v_pk_fma_f32 v[8:9], v[2:3], v[46:47], v[8:9]
	v_add_f32_dpp v4, v4, v4 row_mirror row_mask:0xf bank_mask:0xf bound_ctrl:1
	v_add_f32_e32 v7, v8, v9
	v_fmac_f32_e32 v4, v6, v63
	v_pk_fma_f32 v[0:1], v[52:53], v[4:5], v[0:1] op_sel_hi:[1,0,1]
	v_pk_fma_f32 v[2:3], v[54:55], v[4:5], v[2:3] op_sel_hi:[1,0,1]
	ds_read_b128 v[44:47], v68 offset:5440
	ds_read_b128 v[48:51], v68 offset:5696
	ds_read_b128 v[52:55], v68 offset:5952
	ds_read_b128 v[56:59], v68 offset:6208
	ds_read_b64 v[62:63], v69 offset:5440
	ds_write_b128 v70, v[0:3] offset:4096
	s_waitcnt lgkmcnt(13)
	v_add_f32_dpp v6, v7, v7 quad_perm:[1,0,3,2] row_mask:0xf bank_mask:0xf bound_ctrl:1
	v_pk_mul_f32 v[8:9], v[24:25], v[66:67] op_sel_hi:[1,0]
	v_pk_mul_f32 v[10:11], v[26:27], v[66:67] op_sel_hi:[1,0]
	v_add_f32_dpp v6, v6, v6 quad_perm:[2,3,0,1] row_mask:0xf bank_mask:0xf bound_ctrl:1
	v_pk_fma_f32 v[0:1], v[0:1], v[16:17], v[8:9]
	v_pk_fma_f32 v[2:3], v[2:3], v[18:19], v[10:11]
	v_add_f32_dpp v6, v6, v6 row_half_mirror row_mask:0xf bank_mask:0xf bound_ctrl:1
	v_pk_mul_f32 v[8:9], v[0:1], v[12:13]
	v_pk_fma_f32 v[8:9], v[2:3], v[14:15], v[8:9]
	v_add_f32_dpp v6, v6, v6 row_mirror row_mask:0xf bank_mask:0xf bound_ctrl:1
	v_add_f32_e32 v7, v8, v9
	v_fmac_f32_e32 v6, v4, v65
	v_pk_fma_f32 v[0:1], v[20:21], v[6:7], v[0:1] op_sel_hi:[1,0,1]
	v_pk_fma_f32 v[2:3], v[22:23], v[6:7], v[2:3] op_sel_hi:[1,0,1]
	ds_read_b128 v[12:15], v68 offset:6528
	ds_read_b128 v[16:19], v68 offset:6784
	ds_read_b128 v[20:23], v68 offset:7040
	ds_read_b128 v[24:27], v68 offset:7296
	ds_read_b64 v[64:65], v69 offset:6528
	ds_write_b128 v70, v[0:3] offset:6144
	s_waitcnt lgkmcnt(13)
	v_add_f32_dpp v4, v7, v7 quad_perm:[1,0,3,2] row_mask:0xf bank_mask:0xf bound_ctrl:1
	v_pk_mul_f32 v[8:9], v[40:41], v[60:61] op_sel_hi:[1,0]
	v_pk_mul_f32 v[10:11], v[42:43], v[60:61] op_sel_hi:[1,0]
	v_add_f32_dpp v4, v4, v4 quad_perm:[2,3,0,1] row_mask:0xf bank_mask:0xf bound_ctrl:1
	v_pk_fma_f32 v[0:1], v[0:1], v[32:33], v[8:9]
	v_pk_fma_f32 v[2:3], v[2:3], v[34:35], v[10:11]
	v_add_f32_dpp v4, v4, v4 row_half_mirror row_mask:0xf bank_mask:0xf bound_ctrl:1
	v_pk_mul_f32 v[8:9], v[0:1], v[28:29]
	v_pk_fma_f32 v[8:9], v[2:3], v[30:31], v[8:9]
	v_add_f32_dpp v4, v4, v4 row_mirror row_mask:0xf bank_mask:0xf bound_ctrl:1
	v_add_f32_e32 v7, v8, v9
	v_fmac_f32_e32 v4, v6, v67
	v_pk_fma_f32 v[0:1], v[36:37], v[4:5], v[0:1] op_sel_hi:[1,0,1]
	v_pk_fma_f32 v[2:3], v[38:39], v[4:5], v[2:3] op_sel_hi:[1,0,1]
	ds_read_b128 v[28:31], v68 offset:7616
	ds_read_b128 v[32:35], v68 offset:7872
	ds_read_b128 v[36:39], v68 offset:8128
	ds_read_b128 v[40:43], v68 offset:8384
	ds_read_b64 v[66:67], v69 offset:7616
	ds_write_b128 v70, v[0:3] offset:8192
	s_waitcnt lgkmcnt(13)
	v_add_f32_dpp v6, v7, v7 quad_perm:[1,0,3,2] row_mask:0xf bank_mask:0xf bound_ctrl:1
	v_pk_mul_f32 v[8:9], v[56:57], v[62:63] op_sel_hi:[1,0]
	v_pk_mul_f32 v[10:11], v[58:59], v[62:63] op_sel_hi:[1,0]
	v_add_f32_dpp v6, v6, v6 quad_perm:[2,3,0,1] row_mask:0xf bank_mask:0xf bound_ctrl:1
	v_pk_fma_f32 v[0:1], v[0:1], v[48:49], v[8:9]
	v_pk_fma_f32 v[2:3], v[2:3], v[50:51], v[10:11]
	v_add_f32_dpp v6, v6, v6 row_half_mirror row_mask:0xf bank_mask:0xf bound_ctrl:1
	v_pk_mul_f32 v[8:9], v[0:1], v[44:45]
	v_pk_fma_f32 v[8:9], v[2:3], v[46:47], v[8:9]
	v_add_f32_dpp v6, v6, v6 row_mirror row_mask:0xf bank_mask:0xf bound_ctrl:1
	v_add_f32_e32 v7, v8, v9
	v_fmac_f32_e32 v6, v4, v61
	v_pk_fma_f32 v[0:1], v[52:53], v[6:7], v[0:1] op_sel_hi:[1,0,1]
	v_pk_fma_f32 v[2:3], v[54:55], v[6:7], v[2:3] op_sel_hi:[1,0,1]
	ds_read_b128 v[44:47], v68 offset:8704
	ds_read_b128 v[48:51], v68 offset:8960
	ds_read_b128 v[52:55], v68 offset:9216
	ds_read_b128 v[56:59], v68 offset:9472
	ds_read_b64 v[60:61], v69 offset:8704
	ds_write_b128 v70, v[0:3] offset:10240
	s_waitcnt lgkmcnt(13)
	v_add_f32_dpp v4, v7, v7 quad_perm:[1,0,3,2] row_mask:0xf bank_mask:0xf bound_ctrl:1
	v_pk_mul_f32 v[8:9], v[24:25], v[64:65] op_sel_hi:[1,0]
	v_pk_mul_f32 v[10:11], v[26:27], v[64:65] op_sel_hi:[1,0]
	v_add_f32_dpp v4, v4, v4 quad_perm:[2,3,0,1] row_mask:0xf bank_mask:0xf bound_ctrl:1
	v_pk_fma_f32 v[0:1], v[0:1], v[16:17], v[8:9]
	v_pk_fma_f32 v[2:3], v[2:3], v[18:19], v[10:11]
	v_add_f32_dpp v4, v4, v4 row_half_mirror row_mask:0xf bank_mask:0xf bound_ctrl:1
	v_pk_mul_f32 v[8:9], v[0:1], v[12:13]
	v_pk_fma_f32 v[8:9], v[2:3], v[14:15], v[8:9]
	v_add_f32_dpp v4, v4, v4 row_mirror row_mask:0xf bank_mask:0xf bound_ctrl:1
	v_add_f32_e32 v7, v8, v9
	v_fmac_f32_e32 v4, v6, v63
	v_pk_fma_f32 v[0:1], v[20:21], v[4:5], v[0:1] op_sel_hi:[1,0,1]
	v_pk_fma_f32 v[2:3], v[22:23], v[4:5], v[2:3] op_sel_hi:[1,0,1]
	ds_read_b128 v[12:15], v68 offset:9792
	ds_read_b128 v[16:19], v68 offset:10048
	ds_read_b128 v[20:23], v68 offset:10304
	ds_read_b128 v[24:27], v68 offset:10560
	ds_read_b64 v[62:63], v69 offset:9792
	ds_write_b128 v70, v[0:3] offset:12288
	s_waitcnt lgkmcnt(13)
	v_add_f32_dpp v6, v7, v7 quad_perm:[1,0,3,2] row_mask:0xf bank_mask:0xf bound_ctrl:1
	v_pk_mul_f32 v[8:9], v[40:41], v[66:67] op_sel_hi:[1,0]
	v_pk_mul_f32 v[10:11], v[42:43], v[66:67] op_sel_hi:[1,0]
	v_add_f32_dpp v6, v6, v6 quad_perm:[2,3,0,1] row_mask:0xf bank_mask:0xf bound_ctrl:1
	v_pk_fma_f32 v[0:1], v[0:1], v[32:33], v[8:9]
	v_pk_fma_f32 v[2:3], v[2:3], v[34:35], v[10:11]
	v_add_f32_dpp v6, v6, v6 row_half_mirror row_mask:0xf bank_mask:0xf bound_ctrl:1
	v_pk_mul_f32 v[8:9], v[0:1], v[28:29]
	v_pk_fma_f32 v[8:9], v[2:3], v[30:31], v[8:9]
	v_add_f32_dpp v6, v6, v6 row_mirror row_mask:0xf bank_mask:0xf bound_ctrl:1
	v_add_f32_e32 v7, v8, v9
	v_fmac_f32_e32 v6, v4, v65
	v_pk_fma_f32 v[0:1], v[36:37], v[6:7], v[0:1] op_sel_hi:[1,0,1]
	v_pk_fma_f32 v[2:3], v[38:39], v[6:7], v[2:3] op_sel_hi:[1,0,1]
	ds_read_b128 v[28:31], v68 offset:10880
	ds_read_b128 v[32:35], v68 offset:11136
	ds_read_b128 v[36:39], v68 offset:11392
	ds_read_b128 v[40:43], v68 offset:11648
	ds_read_b64 v[64:65], v69 offset:10880
	ds_write_b128 v70, v[0:3] offset:14336
	s_waitcnt lgkmcnt(13)
	v_add_f32_dpp v4, v7, v7 quad_perm:[1,0,3,2] row_mask:0xf bank_mask:0xf bound_ctrl:1
	v_pk_mul_f32 v[8:9], v[56:57], v[60:61] op_sel_hi:[1,0]
	v_pk_mul_f32 v[10:11], v[58:59], v[60:61] op_sel_hi:[1,0]
	v_add_f32_dpp v4, v4, v4 quad_perm:[2,3,0,1] row_mask:0xf bank_mask:0xf bound_ctrl:1
	v_pk_fma_f32 v[0:1], v[0:1], v[48:49], v[8:9]
	v_pk_fma_f32 v[2:3], v[2:3], v[50:51], v[10:11]
	v_add_f32_dpp v4, v4, v4 row_half_mirror row_mask:0xf bank_mask:0xf bound_ctrl:1
	v_pk_mul_f32 v[8:9], v[0:1], v[44:45]
	v_pk_fma_f32 v[8:9], v[2:3], v[46:47], v[8:9]
	v_add_f32_dpp v4, v4, v4 row_mirror row_mask:0xf bank_mask:0xf bound_ctrl:1
	v_add_f32_e32 v7, v8, v9
	v_fmac_f32_e32 v4, v6, v67
	v_pk_fma_f32 v[0:1], v[52:53], v[4:5], v[0:1] op_sel_hi:[1,0,1]
	v_pk_fma_f32 v[2:3], v[54:55], v[4:5], v[2:3] op_sel_hi:[1,0,1]
	ds_read_b128 v[44:47], v68 offset:11968
	ds_read_b128 v[48:51], v68 offset:12224
	ds_read_b128 v[52:55], v68 offset:12480
	ds_read_b128 v[56:59], v68 offset:12736
	ds_read_b64 v[66:67], v69 offset:11968
	ds_write_b128 v70, v[0:3] offset:16384
	s_waitcnt lgkmcnt(13)
; __device__ __forceinline__ void scan_phase(const ScanArgs& s, char* shm) {
;     ...
;           SLOAD(A, 0); SLOAD(B, 1); SLOAD(C, 2);
;           SSTEP(A, 0); SSTEP(B, 1); SSTEP(C, 2); SSTEP(A, 3); SSTEP(B, 4); SSTEP(C, 5); SSTEP(A, 6); SSTEP(B, 7);
;           SSTEP(C, 8); SSTEP(A, 9); SSTEP(B, 10); SSTEP(C, 11); SSTEP(A, 12); SSTEP(B, 13); SSTEP(C, 14); SSTEP(A, 15);
	v_add_f32_dpp v6, v7, v7 quad_perm:[1,0,3,2] row_mask:0xf bank_mask:0xf bound_ctrl:1
	v_pk_mul_f32 v[8:9], v[24:25], v[62:63] op_sel_hi:[1,0]
	v_pk_mul_f32 v[10:11], v[26:27], v[62:63] op_sel_hi:[1,0]
	v_add_f32_dpp v6, v6, v6 quad_perm:[2,3,0,1] row_mask:0xf bank_mask:0xf bound_ctrl:1
	v_pk_fma_f32 v[0:1], v[0:1], v[16:17], v[8:9]
	v_pk_fma_f32 v[2:3], v[2:3], v[18:19], v[10:11]
	v_add_f32_dpp v6, v6, v6 row_half_mirror row_mask:0xf bank_mask:0xf bound_ctrl:1
	v_pk_mul_f32 v[8:9], v[0:1], v[12:13]
	v_pk_fma_f32 v[8:9], v[2:3], v[14:15], v[8:9]
	v_add_f32_dpp v6, v6, v6 row_mirror row_mask:0xf bank_mask:0xf bound_ctrl:1
	v_add_f32_e32 v7, v8, v9
	v_fmac_f32_e32 v6, v4, v61
	v_pk_fma_f32 v[0:1], v[20:21], v[6:7], v[0:1] op_sel_hi:[1,0,1]
	v_pk_fma_f32 v[2:3], v[22:23], v[6:7], v[2:3] op_sel_hi:[1,0,1]
	ds_read_b128 v[12:15], v68 offset:13056
	ds_read_b128 v[16:19], v68 offset:13312
	ds_read_b128 v[20:23], v68 offset:13568
	ds_read_b128 v[24:27], v68 offset:13824
	ds_read_b64 v[60:61], v69 offset:13056
	ds_write_b128 v70, v[0:3] offset:18432
	s_waitcnt lgkmcnt(13)
	v_add_f32_dpp v4, v7, v7 quad_perm:[1,0,3,2] row_mask:0xf bank_mask:0xf bound_ctrl:1
	v_pk_mul_f32 v[8:9], v[40:41], v[64:65] op_sel_hi:[1,0]
	v_pk_mul_f32 v[10:11], v[42:43], v[64:65] op_sel_hi:[1,0]
	v_add_f32_dpp v4, v4, v4 quad_perm:[2,3,0,1] row_mask:0xf bank_mask:0xf bound_ctrl:1
	v_pk_fma_f32 v[0:1], v[0:1], v[32:33], v[8:9]
	v_pk_fma_f32 v[2:3], v[2:3], v[34:35], v[10:11]
	v_add_f32_dpp v4, v4, v4 row_half_mirror row_mask:0xf bank_mask:0xf bound_ctrl:1
	v_pk_mul_f32 v[8:9], v[0:1], v[28:29]
	v_pk_fma_f32 v[8:9], v[2:3], v[30:31], v[8:9]
	v_add_f32_dpp v4, v4, v4 row_mirror row_mask:0xf bank_mask:0xf bound_ctrl:1
	v_add_f32_e32 v7, v8, v9
	v_fmac_f32_e32 v4, v6, v63
	v_pk_fma_f32 v[0:1], v[36:37], v[4:5], v[0:1] op_sel_hi:[1,0,1]
	v_pk_fma_f32 v[2:3], v[38:39], v[4:5], v[2:3] op_sel_hi:[1,0,1]
	ds_read_b128 v[28:31], v68 offset:14144
	ds_read_b128 v[32:35], v68 offset:14400
	ds_read_b128 v[36:39], v68 offset:14656
	ds_read_b128 v[40:43], v68 offset:14912
	ds_read_b64 v[62:63], v69 offset:14144
	ds_write_b128 v70, v[0:3] offset:20480
	s_waitcnt lgkmcnt(13)
	v_add_f32_dpp v6, v7, v7 quad_perm:[1,0,3,2] row_mask:0xf bank_mask:0xf bound_ctrl:1
	v_pk_mul_f32 v[8:9], v[56:57], v[66:67] op_sel_hi:[1,0]
	v_pk_mul_f32 v[10:11], v[58:59], v[66:67] op_sel_hi:[1,0]
	v_add_f32_dpp v6, v6, v6 quad_perm:[2,3,0,1] row_mask:0xf bank_mask:0xf bound_ctrl:1
	v_pk_fma_f32 v[0:1], v[0:1], v[48:49], v[8:9]
	v_pk_fma_f32 v[2:3], v[2:3], v[50:51], v[10:11]
	v_add_f32_dpp v6, v6, v6 row_half_mirror row_mask:0xf bank_mask:0xf bound_ctrl:1
	v_pk_mul_f32 v[8:9], v[0:1], v[44:45]
	v_pk_fma_f32 v[8:9], v[2:3], v[46:47], v[8:9]
	v_add_f32_dpp v6, v6, v6 row_mirror row_mask:0xf bank_mask:0xf bound_ctrl:1
	v_add_f32_e32 v7, v8, v9
	v_fmac_f32_e32 v6, v4, v65
	v_pk_fma_f32 v[0:1], v[52:53], v[6:7], v[0:1] op_sel_hi:[1,0,1]
	v_pk_fma_f32 v[2:3], v[54:55], v[6:7], v[2:3] op_sel_hi:[1,0,1]
	ds_read_b128 v[44:47], v68 offset:15232
	ds_read_b128 v[48:51], v68 offset:15488
	ds_read_b128 v[52:55], v68 offset:15744
	ds_read_b128 v[56:59], v68 offset:16000
	ds_read_b64 v[64:65], v69 offset:15232
	ds_write_b128 v70, v[0:3] offset:22528
	s_waitcnt lgkmcnt(13)
	v_add_f32_dpp v4, v7, v7 quad_perm:[1,0,3,2] row_mask:0xf bank_mask:0xf bound_ctrl:1
	v_pk_mul_f32 v[8:9], v[24:25], v[60:61] op_sel_hi:[1,0]
	v_pk_mul_f32 v[10:11], v[26:27], v[60:61] op_sel_hi:[1,0]
	v_add_f32_dpp v4, v4, v4 quad_perm:[2,3,0,1] row_mask:0xf bank_mask:0xf bound_ctrl:1
	v_pk_fma_f32 v[0:1], v[0:1], v[16:17], v[8:9]
	v_pk_fma_f32 v[2:3], v[2:3], v[18:19], v[10:11]
	v_add_f32_dpp v4, v4, v4 row_half_mirror row_mask:0xf bank_mask:0xf bound_ctrl:1
	v_pk_mul_f32 v[8:9], v[0:1], v[12:13]
	v_pk_fma_f32 v[8:9], v[2:3], v[14:15], v[8:9]
	v_add_f32_dpp v4, v4, v4 row_mirror row_mask:0xf bank_mask:0xf bound_ctrl:1
	v_add_f32_e32 v7, v8, v9
	v_fmac_f32_e32 v4, v6, v67
	v_pk_fma_f32 v[0:1], v[20:21], v[4:5], v[0:1] op_sel_hi:[1,0,1]
	v_pk_fma_f32 v[2:3], v[22:23], v[4:5], v[2:3] op_sel_hi:[1,0,1]
	ds_read_b128 v[12:15], v68 offset:16320
	ds_read_b128 v[16:19], v68 offset:16576
	ds_read_b128 v[20:23], v68 offset:16832
	ds_read_b128 v[24:27], v68 offset:17088
	ds_read_b64 v[66:67], v69 offset:16320
	ds_write_b128 v70, v[0:3] offset:24576
	s_waitcnt lgkmcnt(13)
	v_add_f32_dpp v6, v7, v7 quad_perm:[1,0,3,2] row_mask:0xf bank_mask:0xf bound_ctrl:1
	v_pk_mul_f32 v[8:9], v[40:41], v[62:63] op_sel_hi:[1,0]
	v_pk_mul_f32 v[10:11], v[42:43], v[62:63] op_sel_hi:[1,0]
	v_add_f32_dpp v6, v6, v6 quad_perm:[2,3,0,1] row_mask:0xf bank_mask:0xf bound_ctrl:1
	v_pk_fma_f32 v[0:1], v[0:1], v[32:33], v[8:9]
	v_pk_fma_f32 v[2:3], v[2:3], v[34:35], v[10:11]
	v_add_f32_dpp v6, v6, v6 row_half_mirror row_mask:0xf bank_mask:0xf bound_ctrl:1
	v_pk_mul_f32 v[8:9], v[0:1], v[28:29]
	v_pk_fma_f32 v[8:9], v[2:3], v[30:31], v[8:9]
	v_add_f32_dpp v6, v6, v6 row_mirror row_mask:0xf bank_mask:0xf bound_ctrl:1
	v_add_f32_e32 v7, v8, v9
	v_fmac_f32_e32 v6, v4, v61
	v_pk_fma_f32 v[0:1], v[36:37], v[6:7], v[0:1] op_sel_hi:[1,0,1]
	v_pk_fma_f32 v[2:3], v[38:39], v[6:7], v[2:3] op_sel_hi:[1,0,1]
	ds_write_b128 v70, v[0:3] offset:26624
	s_waitcnt lgkmcnt(8)
	v_add_f32_dpp v4, v7, v7 quad_perm:[1,0,3,2] row_mask:0xf bank_mask:0xf bound_ctrl:1
	v_pk_mul_f32 v[8:9], v[56:57], v[64:65] op_sel_hi:[1,0]
	v_pk_mul_f32 v[10:11], v[58:59], v[64:65] op_sel_hi:[1,0]
	v_add_f32_dpp v4, v4, v4 quad_perm:[2,3,0,1] row_mask:0xf bank_mask:0xf bound_ctrl:1
	v_pk_fma_f32 v[0:1], v[0:1], v[48:49], v[8:9]
	v_pk_fma_f32 v[2:3], v[2:3], v[50:51], v[10:11]
	v_add_f32_dpp v4, v4, v4 row_half_mirror row_mask:0xf bank_mask:0xf bound_ctrl:1
	v_pk_mul_f32 v[8:9], v[0:1], v[44:45]
	v_pk_fma_f32 v[8:9], v[2:3], v[46:47], v[8:9]
	v_add_f32_dpp v4, v4, v4 row_mirror row_mask:0xf bank_mask:0xf bound_ctrl:1
	v_add_f32_e32 v7, v8, v9
	v_fmac_f32_e32 v4, v6, v63
	v_pk_fma_f32 v[0:1], v[52:53], v[4:5], v[0:1] op_sel_hi:[1,0,1]
	v_pk_fma_f32 v[2:3], v[54:55], v[4:5], v[2:3] op_sel_hi:[1,0,1]
	ds_write_b128 v70, v[0:3] offset:28672
	s_waitcnt lgkmcnt(3)
	v_add_f32_dpp v6, v7, v7 quad_perm:[1,0,3,2] row_mask:0xf bank_mask:0xf bound_ctrl:1
	v_pk_mul_f32 v[8:9], v[24:25], v[66:67] op_sel_hi:[1,0]
	v_pk_mul_f32 v[10:11], v[26:27], v[66:67] op_sel_hi:[1,0]
	v_add_f32_dpp v6, v6, v6 quad_perm:[2,3,0,1] row_mask:0xf bank_mask:0xf bound_ctrl:1
	v_pk_fma_f32 v[0:1], v[0:1], v[16:17], v[8:9]
	v_pk_fma_f32 v[2:3], v[2:3], v[18:19], v[10:11]
	v_add_f32_dpp v6, v6, v6 row_half_mirror row_mask:0xf bank_mask:0xf bound_ctrl:1
	v_pk_mul_f32 v[8:9], v[0:1], v[12:13]
	v_pk_fma_f32 v[8:9], v[2:3], v[14:15], v[8:9]
	v_add_f32_dpp v6, v6, v6 row_mirror row_mask:0xf bank_mask:0xf bound_ctrl:1
	v_add_f32_e32 v7, v8, v9
	v_fmac_f32_e32 v6, v4, v65
	v_pk_fma_f32 v[0:1], v[20:21], v[6:7], v[0:1] op_sel_hi:[1,0,1]
	v_pk_fma_f32 v[2:3], v[22:23], v[6:7], v[2:3] op_sel_hi:[1,0,1]
	ds_write_b128 v70, v[0:3] offset:30720
	s_branch .LBB0_171
